# P5 epilogue pass 1: residual loads in a 3-deep register ring (counted vmcnt leaves the newest store and load in flight)
# baseline (speedup 1.0000x reference)
; __device__ __forceinline__ unsigned cvt_pk_bf16(float lo, float hi) { unsigned r; asm volatile("v_cvt_pk_bf16_f32 %0, %1, %2" : "=v"(r) : "v"(lo), "v"(hi)); return r; }
;     __device__ __forceinline__ void fused(f32x4 (&acc)[2][2][4][2], const Unit& u, int wr, int wc, int fr, int fq, LAS unsigned char* lds, int wid, int lane) const {
;     ...
;           for (int ai = 0; ai < 2; ++ai)
; #pragma unroll
;             for (int m = 0; m < 4; ++m) { const size_t off = (size_t)(row0 + ai * HALF + m * 16) * DM + col0;
; #pragma unroll
;                 for (int bj = 0; bj < 2; ++bj)
; #pragma unroll
;                     for (int n = 0; n < 2; ++n) { const f32x4 xv = *(const f32x4*)(base + off + bj * HALF + n * 16); const f32x4 o = xv + gv[bj][n] * acc[ai][bj][m][n];
;                         u32x2 w; w.x = cvt_pk_bf16(o[0], o[1]); w.y = cvt_pk_bf16(o[2], o[3]); *(u32x2*)(x1b + off + bj * HALF + n * 16) = w; acc[ai][bj][m][n] = o; }
;                 asm volatile("" ::: "memory"); } }
.LBB0_582:
	s_add_u32 s0, s34, 0xd200000
	s_addc_u32 s1, s35, 0
	s_lshl_b32 s11, s7, 5
	s_lshl_b32 s12, s8, 8
	s_or_b32 s11, s12, s11
	s_lshl_b32 s10, s6, 8
	v_and_or_b32 v144, v140, 12, s11
	s_ashr_i32 s11, s6, 3
	s_add_i32 s14, s10, s54
	s_mul_hi_i32 s13, s11, 0x6000
	s_mulk_i32 s11, 0x6000
	s_add_u32 s12, s34, s11
	v_or_b32_e32 v150, s14, v153
	s_addc_u32 s13, s35, s13
	v_ashrrev_i32_e32 v145, 31, v144
	v_ashrrev_i32_e32 v151, 31, v150
	v_lshl_add_u64 v[146:147], v[144:145], 2, s[12:13]
	s_movk_i32 s11, 0x2000
	v_lshlrev_b64 v[130:131], 10, v[150:151]
	v_add_co_u32_e32 v128, vcc, s11, v146
	v_lshl_add_u64 v[148:149], v[130:131], 0, v[144:145]
	s_nop 0
	v_addc_co_u32_e32 v129, vcc, 0, v147, vcc
	v_lshl_add_u64 v[158:159], v[148:149], 2, s[36:37]
	s_barrier
	global_load_dwordx4 v[140:143], v[128:129], off
	global_load_dwordx4 v[136:139], v[128:129], off offset:64
	global_load_dwordx4 v[132:135], v[128:129], off offset:512
	s_nop 0
	global_load_dwordx4 v[128:131], v[128:129], off offset:576
	s_mov_b64 s[98:99], 0x10000
	v_lshl_add_u64 v[178:179], v[158:159], 0, s[98:99]
	s_mov_b64 s[98:99], 0x20000
	v_lshl_add_u64 v[180:181], v[158:159], 0, s[98:99]
	s_mov_b64 s[98:99], 0x30000
	v_lshl_add_u64 v[182:183], v[158:159], 0, s[98:99]
	s_mov_b64 s[98:99], 0x80000
	v_lshl_add_u64 v[184:185], v[158:159], 0, s[98:99]
	s_mov_b64 s[98:99], 0x90000
	v_lshl_add_u64 v[186:187], v[158:159], 0, s[98:99]
	s_mov_b64 s[98:99], 0xa0000
	v_lshl_add_u64 v[188:189], v[158:159], 0, s[98:99]
	s_mov_b64 s[98:99], 0xb0000
	v_lshl_add_u64 v[190:191], v[158:159], 0, s[98:99]
	global_load_dwordx4 v[192:195], v[158:159], off
	global_load_dwordx4 v[196:199], v[158:159], off offset:64
	global_load_dwordx4 v[200:203], v[158:159], off offset:512
	v_lshl_add_u64 v[160:161], v[148:149], 1, s[0:1]
	s_mov_b64 s[12:13], 0x20000
	s_waitcnt vmcnt(2)
	v_pk_fma_f32 v[126:127], v[126:127], v[142:143], v[194:195]
	v_pk_fma_f32 v[124:125], v[124:125], v[140:141], v[192:193]
	s_nop 0
	v_cvt_pk_bf16_f32 v154, v124, v125
	v_cvt_pk_bf16_f32 v155, v126, v127
	global_store_dwordx2 v[160:161], v[154:155], off
	global_load_dwordx4 v[192:195], v[158:159], off offset:576
	s_waitcnt vmcnt(3)
	v_pk_fma_f32 v[122:123], v[122:123], v[138:139], v[198:199]
	v_pk_fma_f32 v[120:121], v[120:121], v[136:137], v[196:197]
	s_nop 0
	v_cvt_pk_bf16_f32 v154, v120, v121
	v_cvt_pk_bf16_f32 v155, v122, v123
	global_store_dwordx2 v[160:161], v[154:155], off offset:32
	global_load_dwordx4 v[196:199], v[178:179], off
	s_waitcnt vmcnt(4)
	v_pk_fma_f32 v[118:119], v[118:119], v[134:135], v[202:203]
	v_pk_fma_f32 v[116:117], v[116:117], v[132:133], v[200:201]
	s_nop 0
	v_cvt_pk_bf16_f32 v154, v116, v117
	v_cvt_pk_bf16_f32 v155, v118, v119
	global_store_dwordx2 v[160:161], v[154:155], off offset:256
	global_load_dwordx4 v[200:203], v[178:179], off offset:64
	v_or_b32_e32 v158, 16, v150
	v_ashrrev_i32_e32 v159, 31, v158
	v_lshlrev_b64 v[158:159], 10, v[158:159]
	v_lshl_add_u64 v[158:159], v[158:159], 0, v[144:145]
	v_lshl_add_u64 v[162:163], v[158:159], 2, s[36:37]
	v_lshl_add_u64 v[158:159], v[158:159], 1, s[0:1]
	s_waitcnt vmcnt(4)
	v_pk_fma_f32 v[110:111], v[110:111], v[130:131], v[194:195]
	v_pk_fma_f32 v[108:109], v[108:109], v[128:129], v[192:193]
	s_nop 0
	v_cvt_pk_bf16_f32 v154, v108, v109
	v_cvt_pk_bf16_f32 v155, v110, v111
	global_store_dwordx2 v[160:161], v[154:155], off offset:288
	global_load_dwordx4 v[192:195], v[178:179], off offset:512
	v_or_b32_e32 v160, 32, v150
	v_ashrrev_i32_e32 v161, 31, v160
	v_lshlrev_b64 v[160:161], 10, v[160:161]
	v_lshl_add_u64 v[160:161], v[160:161], 0, v[144:145]
	v_or_b32_e32 v150, 48, v150
	v_ashrrev_i32_e32 v151, 31, v150
	v_lshlrev_b64 v[150:151], 10, v[150:151]
	v_lshl_add_u64 v[150:151], v[150:151], 0, v[144:145]
	s_waitcnt vmcnt(4)
	v_pk_fma_f32 v[114:115], v[114:115], v[142:143], v[198:199]
	v_pk_fma_f32 v[112:113], v[112:113], v[140:141], v[196:197]
	s_nop 0
	v_cvt_pk_bf16_f32 v154, v112, v113
	v_cvt_pk_bf16_f32 v155, v114, v115
	global_store_dwordx2 v[158:159], v[154:155], off
	global_load_dwordx4 v[196:199], v[178:179], off offset:576
	s_waitcnt vmcnt(4)
	v_pk_fma_f32 v[106:107], v[106:107], v[138:139], v[202:203]
	v_pk_fma_f32 v[104:105], v[104:105], v[136:137], v[200:201]
	s_nop 0
	v_cvt_pk_bf16_f32 v154, v104, v105
	v_cvt_pk_bf16_f32 v155, v106, v107
	global_store_dwordx2 v[158:159], v[154:155], off offset:32
	global_load_dwordx4 v[200:203], v[180:181], off
	s_waitcnt vmcnt(4)
	v_pk_fma_f32 v[102:103], v[102:103], v[134:135], v[194:195]
	v_pk_fma_f32 v[100:101], v[100:101], v[132:133], v[192:193]
	s_nop 0
	v_cvt_pk_bf16_f32 v154, v100, v101
	v_cvt_pk_bf16_f32 v155, v102, v103
	global_store_dwordx2 v[158:159], v[154:155], off offset:256
	global_load_dwordx4 v[192:195], v[180:181], off offset:64
	v_lshl_add_u64 v[162:163], v[160:161], 2, s[36:37]
	s_waitcnt vmcnt(4)
	v_pk_fma_f32 v[94:95], v[94:95], v[130:131], v[198:199]
	v_pk_fma_f32 v[92:93], v[92:93], v[128:129], v[196:197]
	s_nop 0
	v_cvt_pk_bf16_f32 v154, v92, v93
	v_cvt_pk_bf16_f32 v155, v94, v95
	global_store_dwordx2 v[158:159], v[154:155], off offset:288
	global_load_dwordx4 v[196:199], v[180:181], off offset:512
	v_lshl_add_u64 v[158:159], v[160:161], 1, s[0:1]
	v_lshl_add_u64 v[160:161], v[150:151], 2, s[36:37]
	v_lshl_add_u64 v[150:151], v[150:151], 1, s[0:1]
	s_waitcnt vmcnt(4)
	v_pk_fma_f32 v[98:99], v[98:99], v[142:143], v[202:203]
	v_pk_fma_f32 v[96:97], v[96:97], v[140:141], v[200:201]
	s_nop 0
	v_cvt_pk_bf16_f32 v154, v96, v97
	v_cvt_pk_bf16_f32 v155, v98, v99
	global_store_dwordx2 v[158:159], v[154:155], off
	global_load_dwordx4 v[200:203], v[180:181], off offset:576
	s_waitcnt vmcnt(4)
; __device__ __forceinline__ unsigned cvt_pk_bf16(float lo, float hi) { unsigned r; asm volatile("v_cvt_pk_bf16_f32 %0, %1, %2" : "=v"(r) : "v"(lo), "v"(hi)); return r; }
;     __device__ __forceinline__ void fused(f32x4 (&acc)[2][2][4][2], const Unit& u, int wr, int wc, int fr, int fq, LAS unsigned char* lds, int wid, int lane) const {
;     ...
;           for (int ai = 0; ai < 2; ++ai)
; #pragma unroll
;             for (int m = 0; m < 4; ++m) { const size_t off = (size_t)(row0 + ai * HALF + m * 16) * DM + col0;
; #pragma unroll
;                 for (int bj = 0; bj < 2; ++bj)
; #pragma unroll
;                     for (int n = 0; n < 2; ++n) { const f32x4 xv = *(const f32x4*)(base + off + bj * HALF + n * 16); const f32x4 o = xv + gv[bj][n] * acc[ai][bj][m][n];
;                         u32x2 w; w.x = cvt_pk_bf16(o[0], o[1]); w.y = cvt_pk_bf16(o[2], o[3]); *(u32x2*)(x1b + off + bj * HALF + n * 16) = w; acc[ai][bj][m][n] = o; }
;                 asm volatile("" ::: "memory"); } }
	v_pk_fma_f32 v[90:91], v[90:91], v[138:139], v[194:195]
	v_pk_fma_f32 v[88:89], v[88:89], v[136:137], v[192:193]
	s_nop 0
	v_cvt_pk_bf16_f32 v154, v88, v89
	v_cvt_pk_bf16_f32 v155, v90, v91
	global_store_dwordx2 v[158:159], v[154:155], off offset:32
	global_load_dwordx4 v[192:195], v[182:183], off
	s_waitcnt vmcnt(4)
	v_pk_fma_f32 v[86:87], v[86:87], v[134:135], v[198:199]
	v_pk_fma_f32 v[84:85], v[84:85], v[132:133], v[196:197]
	s_nop 0
	v_cvt_pk_bf16_f32 v154, v84, v85
	v_cvt_pk_bf16_f32 v155, v86, v87
	global_store_dwordx2 v[158:159], v[154:155], off offset:256
	global_load_dwordx4 v[196:199], v[182:183], off offset:64
	s_waitcnt vmcnt(4)
	v_pk_fma_f32 v[78:79], v[78:79], v[130:131], v[202:203]
	v_pk_fma_f32 v[76:77], v[76:77], v[128:129], v[200:201]
	s_nop 0
	v_cvt_pk_bf16_f32 v154, v76, v77
	v_cvt_pk_bf16_f32 v155, v78, v79
	global_store_dwordx2 v[158:159], v[154:155], off offset:288
	global_load_dwordx4 v[200:203], v[182:183], off offset:512
	v_lshl_add_u64 v[158:159], v[148:149], 0, s[12:13]
	s_mov_b64 s[12:13], 0x24000
	s_waitcnt vmcnt(4)
	v_pk_fma_f32 v[82:83], v[82:83], v[142:143], v[194:195]
	v_pk_fma_f32 v[80:81], v[80:81], v[140:141], v[192:193]
	s_nop 0
	v_cvt_pk_bf16_f32 v154, v80, v81
	v_cvt_pk_bf16_f32 v155, v82, v83
	global_store_dwordx2 v[150:151], v[154:155], off
	global_load_dwordx4 v[192:195], v[182:183], off offset:576
	s_waitcnt vmcnt(4)
	v_pk_fma_f32 v[74:75], v[74:75], v[138:139], v[198:199]
	v_pk_fma_f32 v[72:73], v[72:73], v[136:137], v[196:197]
	s_nop 0
	v_cvt_pk_bf16_f32 v154, v72, v73
	v_cvt_pk_bf16_f32 v155, v74, v75
	global_store_dwordx2 v[150:151], v[154:155], off offset:32
	global_load_dwordx4 v[196:199], v[184:185], off
	s_waitcnt vmcnt(4)
	v_pk_fma_f32 v[70:71], v[70:71], v[134:135], v[202:203]
	v_pk_fma_f32 v[68:69], v[68:69], v[132:133], v[200:201]
	s_nop 0
	v_cvt_pk_bf16_f32 v154, v68, v69
	v_cvt_pk_bf16_f32 v155, v70, v71
	global_store_dwordx2 v[150:151], v[154:155], off offset:256
	global_load_dwordx4 v[200:203], v[184:185], off offset:64
	v_lshl_add_u64 v[160:161], v[158:159], 2, s[36:37]
	s_waitcnt vmcnt(4)
	v_pk_fma_f32 v[66:67], v[66:67], v[130:131], v[194:195]
	v_pk_fma_f32 v[64:65], v[64:65], v[128:129], v[192:193]
	s_nop 0
	v_cvt_pk_bf16_f32 v154, v64, v65
	v_cvt_pk_bf16_f32 v155, v66, v67
	global_store_dwordx2 v[150:151], v[154:155], off offset:288
	global_load_dwordx4 v[192:195], v[184:185], off offset:512
	v_lshl_add_u64 v[150:151], v[158:159], 1, s[0:1]
	v_lshl_add_u64 v[158:159], v[148:149], 0, s[12:13]
	s_mov_b64 s[12:13], 0x28000
	s_waitcnt vmcnt(4)
	v_pk_fma_f32 v[62:63], v[62:63], v[142:143], v[198:199]
	v_pk_fma_f32 v[60:61], v[60:61], v[140:141], v[196:197]
	s_nop 0
	v_cvt_pk_bf16_f32 v154, v60, v61
	v_cvt_pk_bf16_f32 v155, v62, v63
	global_store_dwordx2 v[150:151], v[154:155], off
	global_load_dwordx4 v[196:199], v[184:185], off offset:576
	s_waitcnt vmcnt(4)
	v_pk_fma_f32 v[58:59], v[58:59], v[138:139], v[202:203]
	v_pk_fma_f32 v[56:57], v[56:57], v[136:137], v[200:201]
	s_nop 0
	v_cvt_pk_bf16_f32 v154, v56, v57
	v_cvt_pk_bf16_f32 v155, v58, v59
	global_store_dwordx2 v[150:151], v[154:155], off offset:32
	global_load_dwordx4 v[200:203], v[186:187], off
	s_waitcnt vmcnt(4)
	v_pk_fma_f32 v[54:55], v[54:55], v[134:135], v[194:195]
	v_pk_fma_f32 v[52:53], v[52:53], v[132:133], v[192:193]
	s_nop 0
	v_cvt_pk_bf16_f32 v154, v52, v53
	v_cvt_pk_bf16_f32 v155, v54, v55
	global_store_dwordx2 v[150:151], v[154:155], off offset:256
	global_load_dwordx4 v[192:195], v[186:187], off offset:64
	v_lshl_add_u64 v[160:161], v[158:159], 2, s[36:37]
	s_waitcnt vmcnt(4)
	v_pk_fma_f32 v[46:47], v[46:47], v[130:131], v[198:199]
	v_pk_fma_f32 v[44:45], v[44:45], v[128:129], v[196:197]
	s_nop 0
	v_cvt_pk_bf16_f32 v154, v44, v45
	v_cvt_pk_bf16_f32 v155, v46, v47
	global_store_dwordx2 v[150:151], v[154:155], off offset:288
	global_load_dwordx4 v[196:199], v[186:187], off offset:512
	v_lshl_add_u64 v[150:151], v[158:159], 1, s[0:1]
	v_lshl_add_u64 v[158:159], v[148:149], 0, s[12:13]
	s_mov_b64 s[12:13], 0x2c000
	s_waitcnt vmcnt(4)
	v_pk_fma_f32 v[50:51], v[50:51], v[142:143], v[202:203]
	v_pk_fma_f32 v[48:49], v[48:49], v[140:141], v[200:201]
	s_nop 0
	v_cvt_pk_bf16_f32 v154, v48, v49
	v_cvt_pk_bf16_f32 v155, v50, v51
	global_store_dwordx2 v[150:151], v[154:155], off
	global_load_dwordx4 v[200:203], v[186:187], off offset:576
	s_waitcnt vmcnt(4)
	v_pk_fma_f32 v[42:43], v[42:43], v[138:139], v[194:195]
	v_pk_fma_f32 v[40:41], v[40:41], v[136:137], v[192:193]
	s_nop 0
	v_cvt_pk_bf16_f32 v154, v40, v41
	v_cvt_pk_bf16_f32 v155, v42, v43
	global_store_dwordx2 v[150:151], v[154:155], off offset:32
	global_load_dwordx4 v[192:195], v[188:189], off
	s_waitcnt vmcnt(4)
; __device__ __forceinline__ unsigned cvt_pk_bf16(float lo, float hi) { unsigned r; asm volatile("v_cvt_pk_bf16_f32 %0, %1, %2" : "=v"(r) : "v"(lo), "v"(hi)); return r; }
;     __device__ __forceinline__ void run(const f32x4 (&v)[2][2][4][2], const Unit& u, int wr, int wc, int fr, int fq, LAS unsigned char* lds, int wid, int lane) const {
;     ...
;         for (int ai = 0; ai < 2; ++ai)
; #pragma unroll
;             for (int m = 0; m < 4; ++m) { float s = 0.f;
; #pragma unroll
;                 for (int bj = 0; bj < 2; ++bj)
; #pragma unroll
;                     for (int n = 0; n < 2; ++n) { const f32x4 x = v[ai][bj][m][n]; s += (x[0] * x[0] + x[1] * x[1]) + (x[2] * x[2] + x[3] * x[3]); }
;                 s += __shfl_xor(s, 16); s += __shfl_xor(s, 32);
;                 if (fq == 0) P[(ai * HALF + wr * 64 + m * 16 + fr) * 4 + wc] = s; }
;     __device__ __forceinline__ void fused(f32x4 (&acc)[2][2][4][2], const Unit& u, int wr, int wc, int fr, int fq, LAS unsigned char* lds, int wid, int lane) const {
;     ...
;                 for (int bj = 0; bj < 2; ++bj)
; #pragma unroll
;                     for (int n = 0; n < 2; ++n) { const f32x4 xv = *(const f32x4*)(base + off + bj * HALF + n * 16); const f32x4 o = xv + gv[bj][n] * acc[ai][bj][m][n];
;                         u32x2 w; w.x = cvt_pk_bf16(o[0], o[1]); w.y = cvt_pk_bf16(o[2], o[3]); *(u32x2*)(x1b + off + bj * HALF + n * 16) = w; acc[ai][bj][m][n] = o; }
;                 asm volatile("" ::: "memory"); } }
	v_pk_fma_f32 v[38:39], v[38:39], v[134:135], v[198:199]
	v_pk_fma_f32 v[36:37], v[36:37], v[132:133], v[196:197]
	s_nop 0
	v_cvt_pk_bf16_f32 v154, v36, v37
	v_cvt_pk_bf16_f32 v155, v38, v39
	global_store_dwordx2 v[150:151], v[154:155], off offset:256
	global_load_dwordx4 v[196:199], v[188:189], off offset:64
	v_lshl_add_u64 v[160:161], v[158:159], 2, s[36:37]
	s_waitcnt vmcnt(4)
	v_pk_fma_f32 v[30:31], v[30:31], v[130:131], v[202:203]
	v_pk_fma_f32 v[28:29], v[28:29], v[128:129], v[200:201]
	s_nop 0
	v_cvt_pk_bf16_f32 v154, v28, v29
	v_cvt_pk_bf16_f32 v155, v30, v31
	global_store_dwordx2 v[150:151], v[154:155], off offset:288
	global_load_dwordx4 v[200:203], v[188:189], off offset:512
	v_lshl_add_u64 v[150:151], v[158:159], 1, s[0:1]
	v_lshl_add_u64 v[158:159], v[148:149], 0, s[12:13]
	s_waitcnt vmcnt(4)
	v_pk_fma_f32 v[34:35], v[34:35], v[142:143], v[194:195]
	v_pk_fma_f32 v[32:33], v[32:33], v[140:141], v[192:193]
	s_nop 0
	v_cvt_pk_bf16_f32 v154, v32, v33
	v_cvt_pk_bf16_f32 v155, v34, v35
	global_store_dwordx2 v[150:151], v[154:155], off
	global_load_dwordx4 v[192:195], v[188:189], off offset:576
	s_waitcnt vmcnt(4)
	v_pk_fma_f32 v[26:27], v[26:27], v[138:139], v[198:199]
	v_pk_fma_f32 v[24:25], v[24:25], v[136:137], v[196:197]
	s_nop 0
	v_cvt_pk_bf16_f32 v154, v24, v25
	v_cvt_pk_bf16_f32 v155, v26, v27
	global_store_dwordx2 v[150:151], v[154:155], off offset:32
	s_waitcnt vmcnt(3)
	v_pk_fma_f32 v[22:23], v[22:23], v[134:135], v[202:203]
	v_pk_fma_f32 v[20:21], v[20:21], v[132:133], v[200:201]
	s_nop 0
	v_cvt_pk_bf16_f32 v154, v20, v21
	v_cvt_pk_bf16_f32 v155, v22, v23
	global_store_dwordx2 v[150:151], v[154:155], off offset:256
	v_lshl_add_u64 v[160:161], v[158:159], 2, s[36:37]
	s_waitcnt vmcnt(2)
	v_pk_fma_f32 v[14:15], v[14:15], v[130:131], v[194:195]
	v_pk_fma_f32 v[12:13], v[12:13], v[128:129], v[192:193]
	v_lshl_add_u64 v[154:155], v[158:159], 1, s[0:1]
	v_cvt_pk_bf16_f32 v148, v12, v13
	v_cvt_pk_bf16_f32 v149, v14, v15
	global_store_dwordx2 v[150:151], v[148:149], off offset:288
	global_load_dwordx4 v[148:151], v[160:161], off
	s_lshl_b32 s0, s7, 2
	s_add_i32 s7, s0, 0
	s_waitcnt vmcnt(0)
	v_pk_fma_f32 v[142:143], v[18:19], v[142:143], v[150:151]
	v_pk_fma_f32 v[140:141], v[16:17], v[140:141], v[148:149]
	s_nop 0
	v_cvt_pk_bf16_f32 v16, v140, v141
	v_cvt_pk_bf16_f32 v17, v142, v143
	global_store_dwordx2 v[154:155], v[16:17], off
	global_load_dwordx4 v[148:151], v[160:161], off offset:64
	s_waitcnt vmcnt(0)
	v_pk_fma_f32 v[16:17], v[10:11], v[138:139], v[150:151]
	v_pk_fma_f32 v[18:19], v[8:9], v[136:137], v[148:149]
	s_nop 0
	v_cvt_pk_bf16_f32 v8, v18, v19
	v_cvt_pk_bf16_f32 v9, v16, v17
	global_store_dwordx2 v[154:155], v[8:9], off offset:32
	global_load_dwordx4 v[136:139], v[160:161], off offset:512
	s_waitcnt vmcnt(0)
	v_pk_fma_f32 v[8:9], v[6:7], v[134:135], v[138:139]
	v_pk_fma_f32 v[10:11], v[4:5], v[132:133], v[136:137]
	v_mul_f32_e32 v7, v127, v127
	v_cvt_pk_bf16_f32 v4, v10, v11
	v_cvt_pk_bf16_f32 v5, v8, v9
	global_store_dwordx2 v[154:155], v[4:5], off offset:256
	global_load_dwordx4 v[136:139], v[160:161], off offset:576
	v_mbcnt_lo_u32_b32 v4, -1, 0
	v_mbcnt_hi_u32_b32 v4, -1, v4
	v_and_b32_e32 v6, 64, v4
	v_xor_b32_e32 v5, 16, v4
	v_add_u32_e32 v6, 64, v6
	v_cmp_lt_i32_e32 vcc, v5, v6
	v_fmac_f32_e32 v7, v126, v126
	v_mul_f32_e32 v134, v123, v123
	v_cndmask_b32_e32 v5, v4, v5, vcc
	v_lshlrev_b32_e32 v133, 2, v5
	v_mul_f32_e32 v5, v125, v125
	v_fmac_f32_e32 v5, v124, v124
	v_add_f32_e32 v5, v5, v7
	v_mul_f32_e32 v7, v121, v121
	v_fmac_f32_e32 v7, v120, v120
	v_fmac_f32_e32 v134, v122, v122
	v_add_f32_e32 v7, v7, v134
	v_add_f32_e32 v5, v5, v7
	v_mul_f32_e32 v7, v117, v117
	v_mul_f32_e32 v134, v119, v119
	v_fmac_f32_e32 v7, v116, v116
	v_fmac_f32_e32 v134, v118, v118
	v_add_f32_e32 v7, v7, v134
	v_add_f32_e32 v5, v5, v7
	v_mul_f32_e32 v7, v109, v109
	v_mul_f32_e32 v134, v111, v111
	v_fmac_f32_e32 v7, v108, v108
	v_fmac_f32_e32 v134, v110, v110
	v_add_f32_e32 v7, v7, v134
	v_add_f32_e32 v5, v5, v7
	ds_bpermute_b32 v7, v133, v5
	v_xor_b32_e32 v134, 32, v4
	v_cmp_lt_i32_e32 vcc, v134, v6
	v_and_b32_e32 v132, 63, v170
	s_waitcnt lgkmcnt(0)
	v_add_f32_e32 v135, v5, v7
	v_cndmask_b32_e32 v4, v4, v134, vcc
	v_lshlrev_b32_e32 v134, 2, v4
	v_cmp_gt_u32_e32 vcc, 16, v132
	s_waitcnt vmcnt(0)
	v_pk_fma_f32 v[6:7], v[0:1], v[128:129], v[136:137]
	s_nop 0
	v_cvt_pk_bf16_f32 v0, v6, v7
	v_pk_fma_f32 v[4:5], v[2:3], v[130:131], v[138:139]
	s_nop 0
	v_cvt_pk_bf16_f32 v1, v4, v5
	global_store_dwordx2 v[154:155], v[0:1], off offset:288
	ds_bpermute_b32 v0, v134, v135
	s_and_saveexec_b64 s[0:1], vcc
	v_readlane_b32 s56, v240, 6
	v_readlane_b32 s58, v240, 8
	v_readlane_b32 s57, v240, 7
	v_readlane_b32 s59, v240, 9
	s_cbranch_execz .LBB0_584
	s_lshl_b32 s11, s51, 10
	s_add_i32 s11, s7, s11
	v_lshl_add_u32 v1, v153, 4, s11
	s_waitcnt lgkmcnt(0)
	v_add_f32_e32 v0, v135, v0
	ds_write_b32 v1, v0
